# scan: chain-to-XCD local workgroup mapping + 2-rows-per-lane compute + deeper staging prefetch
# speedup vs baseline: 1.0162x; 1.0162x over previous
.LBB0_166:
	s_or_b64 exec, exec, s[42:43]
	v_readlane_b32 s4, v253, 3
	v_readlane_b32 s5, v253, 4
	s_lshl_b32 s16, s4, 4
	v_readlane_b32 s13, v253, 0
	s_mul_i32 s0, s5, s4
	s_and_b32 s100, s13, 7
	s_bfe_u32 s101, s13, 0x20003
	s_lshl_b32 s100, s100, 5
	s_lshl_b32 s101, s101, 3
	s_or_b32 s100, s100, s101
	s_lshr_b32 s101, s13, 5
	s_or_b32 s100, s100, s101
	s_lshl_b32 s101, s100, 3
	s_cmpk_lt_i32 s13, 0x340
	v_readlane_b32 s2, v253, 1
	s_mul_i32 s65, s0, s31
	s_cselect_b64 s[0:1], -1, 0
	v_readlane_b32 s3, v253, 2
	v_writelane_b32 v253, s0, 6
	s_waitcnt lgkmcnt(0)
	s_barrier
	v_writelane_b32 v253, s1, 7
	s_ashr_i32 s0, s13, 31
	v_writelane_b32 v253, s0, 8
	s_lshr_b32 s0, s0, 29
	s_add_i32 s0, s13, s0
	s_ashr_i32 s6, s0, 3
	s_and_b32 s0, s0, -8
	s_sub_i32 s7, s13, s0
	s_ashr_i32 s0, s4, 31
	s_cmpk_lt_i32 s13, 0x300
	s_load_dwordx2 s[66:67], s[2:3], 0x118
	v_writelane_b32 v253, s0, 9
	s_cselect_b64 s[0:1], -1, 0
	v_writelane_b32 v253, s0, 10
	s_lshr_b32 s48, s100, 3
	s_mov_b32 s49, 0
	v_writelane_b32 v253, s1, 11
	s_lshr_b32 s0, s100, 7
	s_bfe_u32 s1, s100, 0x40003
	v_readlane_b32 s14, v253, 5
	s_lshl_b32 s4, s0, 13
	s_lshl_b32 s18, s1, 6
	s_and_b32 s2, s101, 56
	s_lshl_b32 s15, s0, 12
	s_lshl_b32 s0, s1, 4
	v_writelane_b32 v253, s2, 12
	s_waitcnt lgkmcnt(0)
	s_add_u32 s0, s66, s0
	v_writelane_b32 v253, s0, 13
	s_addc_u32 s0, s67, 0
	v_writelane_b32 v253, s0, 14
	s_or_b32 s0, s4, 8
	s_lshl_b64 s[2:3], s[48:49], 14
	v_writelane_b32 v253, s0, 15
	s_add_u32 s0, s66, s2
	v_writelane_b32 v253, s0, 16
	s_addc_u32 s0, s67, s3
	v_writelane_b32 v253, s0, 17
	s_lshl_b32 s0, s100, 9
	s_and_b32 s20, s0, 0xe00
	s_and_b32 s0, s101, 0x3c0
	v_writelane_b32 v253, s0, 18
	s_or_b32 s0, s4, 0x1000
	v_writelane_b32 v253, s0, 19
	v_writelane_b32 v253, s4, 20
	s_or_b32 s0, s4, s20
	v_writelane_b32 v253, s0, 21
	s_bitset1_b32 s0, 12
	s_cmpk_lt_i32 s13, 0x2c0
	v_writelane_b32 v253, s0, 22
	s_cselect_b64 s[2:3], -1, 0
	v_writelane_b32 v253, s2, 23
	s_cmpk_lt_i32 s13, 0x100
	s_movk_i32 s4, 0x61
	v_writelane_b32 v253, s3, 24
	s_cselect_b64 s[2:3], -1, 0
	s_lshl_b32 s0, s7, 5
	v_writelane_b32 v253, s2, 25
	s_cmpk_lt_i32 s13, 0x400
	s_movk_i32 s5, 0x59
	v_writelane_b32 v253, s3, 26
	s_cselect_b64 s[2:3], -1, 0
	v_writelane_b32 v253, s2, 27
	s_cmp_lg_u64 s[66:67], 0
	s_mov_b32 s19, s49
	v_writelane_b32 v253, s3, 28
	s_cselect_b64 s[2:3], -1, 0
	v_writelane_b32 v253, s2, 29
	s_cmpk_lt_i32 s13, 0x580
	v_mbcnt_lo_u32_b32 v0, -1, 0
	v_writelane_b32 v253, s3, 30
	s_cselect_b64 s[2:3], -1, 0
	v_writelane_b32 v253, s2, 31
	s_cmp_lt_i32 s7, 0
	s_cselect_b32 s4, s4, 0x60
	v_writelane_b32 v253, s3, 32
	s_movk_i32 s3, 0x69
	s_mul_i32 s2, s7, 33
	s_cselect_b32 s3, s3, 0x68
	s_mul_i32 s3, s7, s3
	s_cselect_b32 s8, s2, s0
	s_movk_i32 s0, 0xb1
	s_cselect_b32 s5, s5, 0x58
	s_cselect_b32 s9, s0, 0xb0
	s_add_i32 s3, s3, s6
	s_mul_hi_i32 s0, s3, 0x4ec4ec4f
	s_lshr_b32 s2, s0, 31
	s_ashr_i32 s0, s0, 5
	s_add_i32 s0, s0, s2
	s_mul_i32 s2, s0, 0x68
	s_sub_i32 s2, s3, s2
	s_lshl_b32 s10, s0, 3
	s_bfe_i32 s0, s2, 0x80000
	s_bfe_u32 s0, s0, 0x3000c
	s_add_i32 s3, s2, s0
	s_bfe_i32 s0, s3, 0x80000
	s_and_b32 s3, s3, 0xf8
	s_sub_i32 s2, s2, s3
	s_sext_i32_i8 s2, s2
	s_sext_i32_i16 s11, s0
	s_add_i32 s10, s10, s2
	s_lshr_b32 s0, s11, 3
	s_ashr_i32 s2, s11, 3
	s_ashr_i32 s11, s10, 31
	v_writelane_b32 v253, s2, 33
	s_lshl_b64 s[2:3], s[10:11], 19
	v_writelane_b32 v253, s2, 34
	s_ashr_i32 s17, s16, 31
	v_mbcnt_hi_u32_b32 v229, -1, v0
	v_writelane_b32 v253, s3, 35
	s_mov_b32 s2, s10
	v_writelane_b32 v253, s2, 36
	s_mov_b32 s72, 2.0
	s_mov_b32 s52, 0x41000000
	v_writelane_b32 v253, s3, 37
	s_ashr_i32 s2, s10, 5
	s_ashr_i32 s3, s2, 31
	s_lshl_b64 s[2:3], s[2:3], 11
	v_writelane_b32 v253, s2, 38
	s_mov_b32 s56, 0x41200000
	s_mov_b32 s76, 0x41800000
	v_writelane_b32 v253, s3, 39
	s_bfe_i64 s[2:3], s[0:1], 0x100000
	s_mul_i32 s0, s7, s4
	v_writelane_b32 v253, s2, 40
	s_add_i32 s0, s0, s6
	s_mov_b32 s92, 0x41900000
	v_writelane_b32 v253, s3, 41
	s_mul_hi_i32 s2, s0, 0x2aaaaaab
	s_lshr_b32 s3, s2, 31
	s_ashr_i32 s2, s2, 4
	s_add_i32 s2, s2, s3
	s_mul_i32 s3, s2, 0x60
	s_sub_i32 s3, s0, s3
	s_bfe_i32 s0, s3, 0x80000
	s_bfe_u32 s0, s0, 0x3000c
	s_add_i32 s4, s3, s0
	s_bfe_i32 s0, s4, 0x80000
	s_and_b32 s4, s4, 0xf8
	s_sub_i32 s3, s3, s4
	s_lshl_b32 s2, s2, 3
	s_sext_i32_i16 s10, s0
	s_sext_i32_i8 s3, s3
	s_mul_i32 s4, s7, s5
	s_add_i32 s22, s2, s3
	s_ashr_i32 s2, s10, 3
	s_add_i32 s4, s4, s6
	v_writelane_b32 v253, s2, 42
	s_mul_hi_i32 s2, s4, 0x2e8ba2e9
	s_lshr_b32 s3, s2, 31
	s_ashr_i32 s2, s2, 4
	s_add_i32 s2, s2, s3
	s_mul_i32 s3, s2, 0x58
	s_sub_i32 s3, s4, s3
	s_lshl_b32 s5, s2, 3
	s_bfe_i32 s2, s3, 0x80000
	s_bfe_u32 s2, s2, 0x3000c
	s_add_i32 s4, s3, s2
	s_bfe_i32 s2, s4, 0x80000
	s_and_b32 s4, s4, 0xf8
	s_sub_i32 s3, s3, s4
	s_lshr_b32 s0, s10, 3
	s_sext_i32_i16 s10, s2
	s_sext_i32_i8 s3, s3
	s_add_i32 s24, s5, s3
	s_ashr_i32 s3, s10, 3
	v_writelane_b32 v253, s3, 43
	s_add_i32 s3, s8, s6
	s_ashr_i32 s8, s3, 31
	s_lshr_b32 s4, s8, 26
	s_add_i32 s4, s3, s4
	s_ashr_i32 s5, s4, 6
	s_and_b32 s4, s4, 0xffc0
	s_lshr_b32 s2, s10, 3
	s_sub_i32 s10, s3, s4
	s_bfe_i32 s4, s10, 0x80000
	s_bfe_u32 s4, s4, 0x3000c
	s_add_i32 s11, s10, s4
	s_bfe_i32 s4, s11, 0x80000
	s_and_b32 s11, s11, 0xf8
	s_sub_i32 s10, s10, s11
	s_lshl_b32 s5, s5, 3
	s_sext_i32_i16 s12, s4
	s_sext_i32_i8 s10, s10
	s_add_i32 s26, s5, s10
	s_ashr_i32 s5, s12, 3
	v_writelane_b32 v253, s5, 44
	s_mov_b32 s10, s26
	s_ashr_i32 s27, s26, 31
	v_writelane_b32 v253, s10, 45
	s_lshr_b32 s4, s12, 3
	s_bfe_i64 s[4:5], s[4:5], 0x100000
	v_writelane_b32 v253, s11, 46
	s_lshl_b64 s[10:11], s[26:27], 19
	v_writelane_b32 v253, s10, 47
	s_lshl_b64 s[4:5], s[4:5], 9
	s_ashr_i32 s23, s22, 31
	v_writelane_b32 v253, s11, 48
	v_writelane_b32 v253, s4, 49
	s_ashr_i32 s25, s24, 31
	s_mov_b32 s62, 0x41c00000
	v_writelane_b32 v253, s5, 50
	s_lshr_b32 s4, s8, 27
	s_add_i32 s4, s3, s4
	s_ashr_i32 s5, s4, 5
	s_and_b32 s4, s4, 0xffe0
	s_sub_i32 s3, s3, s4
	s_bfe_i32 s4, s3, 0x80000
	s_bfe_u32 s4, s4, 0x3000c
	s_add_i32 s8, s3, s4
	s_bfe_i32 s4, s8, 0x80000
	s_and_b32 s8, s8, 0xf8
	s_sub_i32 s3, s3, s8
	s_lshl_b32 s5, s5, 3
	s_sext_i32_i16 s10, s4
	s_sext_i32_i8 s3, s3
	s_add_i32 s26, s5, s3
	s_ashr_i32 s3, s10, 3
	v_writelane_b32 v253, s3, 51
	s_mul_i32 s3, s7, s9
	s_add_i32 s3, s3, s6
	s_mul_hi_i32 s5, s3, 0x2e8ba2e9
	s_lshr_b32 s6, s5, 31
	s_ashr_i32 s5, s5, 5
	s_add_i32 s5, s5, s6
	s_lshl_b32 s7, s5, 3
	s_mulk_i32 s5, 0xb0
	s_sub_i32 s3, s3, s5
	s_bfe_u32 s5, s3, 0x3001c
	s_add_i32 s5, s3, s5
	s_sext_i32_i16 s8, s5
	s_and_b32 s5, s5, 0xfff8
	s_sub_i32 s3, s3, s5
	s_sext_i32_i16 s3, s3
	s_lshr_b32 s4, s10, 3
	s_add_i32 s10, s7, s3
	s_lshr_b32 s6, s8, 3
	s_ashr_i32 s3, s8, 3
	s_ashr_i32 s8, s10, 5
	s_ashr_i32 s9, s8, 31
	v_writelane_b32 v253, s3, 52
	s_lshl_b64 s[8:9], s[8:9], 11
	v_writelane_b32 v253, s8, 53
	s_bfe_i64 s[6:7], s[6:7], 0x100000
	s_bfe_i64 s[4:5], s[4:5], 0x100000
	v_writelane_b32 v253, s9, 54
	v_writelane_b32 v253, s6, 55
	s_bfe_i64 s[2:3], s[2:3], 0x100000
	s_ashr_i32 s11, s10, 31
	v_writelane_b32 v253, s7, 56
	v_writelane_b32 v253, s4, 57
	s_ashr_i32 s27, s26, 31
	s_mov_b32 s74, 0x41d00000
	v_writelane_b32 v253, s5, 58
	s_bfe_i64 s[4:5], s[0:1], 0x100000
	v_writelane_b32 v253, s4, 59
	s_ashr_i32 s0, s26, 5
	s_mov_b32 s68, 0x42680000
	v_writelane_b32 v253, s5, 60
	s_ashr_i32 s4, s24, 5
	s_ashr_i32 s5, s4, 31
	s_lshl_b64 s[4:5], s[4:5], 11
	v_writelane_b32 v253, s4, 61
	s_mov_b32 s82, 0x42600000
	s_mov_b32 s90, 0x42480000
	v_writelane_b32 v253, s5, 62
	v_writelane_b32 v253, s2, 63
	s_mov_b32 s70, 0x42400000
	s_mov_b32 s60, 0x42280000
	v_writelane_b32 v254, s3, 0
	v_writelane_b32 v254, s0, 1
	s_ashr_i32 s0, s0, 31
	v_writelane_b32 v254, s0, 2
	s_mov_b32 s0, s10
	v_writelane_b32 v254, s0, 3
	s_lshl_b64 s[2:3], s[10:11], 19
	s_mov_b32 s78, 0x42200000
	v_writelane_b32 v254, s1, 4
	v_writelane_b32 v254, s2, 5
	s_mov_b32 s0, s22
	s_mov_b32 s84, 0x42080000
	v_writelane_b32 v254, s3, 6
	v_writelane_b32 v254, s0, 7
	s_lshl_b64 s[2:3], s[22:23], 17
	s_mov_b32 s94, 0x42000000
	v_writelane_b32 v254, s1, 8
	v_writelane_b32 v254, s2, 9
	s_mov_b32 s0, s24
	v_and_b32_e32 v0, 64, v229
	v_writelane_b32 v254, s3, 10
	v_writelane_b32 v254, s0, 11
	s_lshl_b64 s[2:3], s[24:25], 19
	s_lshl_b64 s[24:25], s[16:17], 12
	v_writelane_b32 v254, s1, 12
	v_writelane_b32 v254, s2, 13
	s_mov_b32 s0, s26
	v_mov_b32_e32 v177, 0
	v_writelane_b32 v254, s3, 14
	v_writelane_b32 v254, s0, 15
	s_lshl_b64 s[2:3], s[26:27], 19
	v_mov_b32_e32 v224, 0x358637bd
	v_writelane_b32 v254, s1, 16
	v_writelane_b32 v254, s2, 17
	s_mov_b32 s0, s16
	v_mov_b32_e32 v225, 0x1000
	v_writelane_b32 v254, s3, 18
	v_writelane_b32 v254, s0, 19
	s_add_u32 s2, s66, 16
	s_addc_u32 s3, s67, 0
	v_writelane_b32 v254, s1, 20
	v_writelane_b32 v254, s2, 21
	s_lshl_b32 s0, s1, 7
	s_ashr_i32 s87, s86, 31
	v_writelane_b32 v254, s3, 22
	s_and_b32 s2, s100, 7
	s_lshl_b32 s3, s2, 4
	s_or_b32 s0, s0, s3
	v_writelane_b32 v254, s0, 23
	s_lshl_b32 s0, s1, 8
	s_lshl_b32 s1, s2, 5
	s_or_b32 s0, s0, s1
	v_writelane_b32 v254, s0, 24
	v_writelane_b32 v254, s18, 25
	s_or_b32 s0, s15, s20
	s_or_b32 s0, s0, 8
	v_writelane_b32 v254, s19, 26
	v_writelane_b32 v254, s15, 27
	v_writelane_b32 v254, s20, 28
	v_writelane_b32 v254, s0, 29
	s_add_i32 s0, s14, 1
	v_writelane_b32 v254, s0, 30
	s_lshl_b64 s[0:1], s[86:87], 11
	v_writelane_b32 v254, s0, 31
	v_mov_b32_e32 v226, 0x2000
	s_mov_b32 s73, 0x40400000
	v_writelane_b32 v254, s1, 32
	s_lshl_b64 s[0:1], s[86:87], 8
	s_add_u32 s2, s66, 0x4000
	s_addc_u32 s3, s67, 0
	v_writelane_b32 v254, s2, 33
	s_mov_b32 s53, 0x41100000
	s_mov_b32 s57, 0x41300000
	v_writelane_b32 v254, s3, 34
	s_add_u32 s2, s38, 0xc00
	s_addc_u32 s3, s39, 0
	v_writelane_b32 v254, s2, 35
	s_mov_b32 s77, 0x41880000
	s_mov_b32 s93, 0x41980000
	v_writelane_b32 v254, s3, 36
	s_add_i32 s2, 0, 0x22ff0
	v_writelane_b32 v254, s2, 37
	s_add_i32 s2, 0, 0x22ff4
	v_writelane_b32 v254, s2, 38
	s_add_i32 s2, 0, 0x1e310
	v_writelane_b32 v254, s2, 39
	s_add_i32 s2, 0, 0x11510
	v_writelane_b32 v254, s2, 40
	s_add_i32 s2, 0, 0x11100
	v_writelane_b32 v254, s2, 41
	s_add_i32 s2, 0, 0x11500
	v_writelane_b32 v254, s2, 42
	s_add_i32 s2, 0, 0x9000
	v_writelane_b32 v254, s2, 43
	v_writelane_b32 v254, s86, 44
	s_mov_b32 s63, 0x41c80000
	s_mov_b32 s75, 0x41d80000
	v_writelane_b32 v254, s87, 45
	v_writelane_b32 v254, s66, 46
	s_mov_b32 s69, 0x426c0000
	s_mov_b32 s83, 0x42640000
	v_writelane_b32 v254, s67, 47
	v_writelane_b32 v254, s65, 48
	v_writelane_b32 v254, s24, 49
	s_mov_b32 s91, 0x424c0000
	s_mov_b32 s71, 0x42440000
	v_writelane_b32 v254, s25, 50
	v_writelane_b32 v254, s0, 51
	s_mov_b32 s61, 0x422c0000
	s_mov_b32 s79, 0x42240000
	s_mov_b32 s85, 0x420c0000
	s_mov_b32 s95, 0x42040000
	v_add_u32_e32 v230, 64, v0
	v_xor_b32_e32 v231, 1, v229
	v_xor_b32_e32 v232, 2, v229
	v_xor_b32_e32 v233, 4, v229
	v_xor_b32_e32 v234, 8, v229
	v_xor_b32_e32 v235, 16, v229
	v_xor_b32_e32 v236, 32, v229
	v_mov_b32_e32 v179, 1.0
	v_mov_b64_e32 v[180:181], 0x100
	v_mov_b64_e32 v[182:183], 0xff
	v_mov_b32_e32 v237, 0xff800000
	v_mov_b32_e32 v250, 0x400
	v_mov_b32_e32 v227, 0x800
	v_mov_b32_e32 v228, 0x4000
	v_mov_b32_e32 v252, 0x8000
	v_mov_b64_e32 v[184:185], 0x580
	v_mov_b64_e32 v[186:187], 0x57f
	s_mov_b32 s18, 0x800000
	s_movk_i32 s22, 0x3fff
	s_movk_i32 s43, 0x90
	s_movk_i32 s64, 0x44
	s_mov_b32 s26, 0
	s_mov_b64 s[96:97], 0x80
	s_mov_b64 s[80:81], 0x2000
	v_writelane_b32 v254, s1, 52
	s_branch .LBB0_170

	.amdhsa_kernel _Z10fwd_kernel1P
		.amdhsa_group_segment_fixed_size 0
		.amdhsa_private_segment_fixed_size 0
		.amdhsa_kernarg_size 544
		.amdhsa_user_sgpr_count 2
		.amdhsa_user_sgpr_dispatch_ptr 0
		.amdhsa_user_sgpr_queue_ptr 0
		.amdhsa_user_sgpr_kernarg_segment_ptr 1
		.amdhsa_user_sgpr_dispatch_id 0
		.amdhsa_user_sgpr_kernarg_preload_length 0
		.amdhsa_user_sgpr_kernarg_preload_offset 0
		.amdhsa_user_sgpr_private_segment_size 0
		.amdhsa_uses_dynamic_stack 0
		.amdhsa_enable_private_segment 0
		.amdhsa_system_sgpr_workgroup_id_x 1
		.amdhsa_system_sgpr_workgroup_id_y 0
		.amdhsa_system_sgpr_workgroup_id_z 0
		.amdhsa_system_sgpr_workgroup_info 0
		.amdhsa_system_vgpr_workitem_id 2
		.amdhsa_next_free_vgpr 256
		.amdhsa_next_free_sgpr 102
		.amdhsa_accum_offset 256
		.amdhsa_reserve_vcc 1
		.amdhsa_float_round_mode_32 0
		.amdhsa_float_round_mode_16_64 0
		.amdhsa_float_denorm_mode_32 3
		.amdhsa_float_denorm_mode_16_64 3
		.amdhsa_dx10_clamp 1
		.amdhsa_ieee_mode 1
		.amdhsa_fp16_overflow 0
		.amdhsa_tg_split 0
		.amdhsa_exception_fp_ieee_invalid_op 0
		.amdhsa_exception_fp_denorm_src 0
		.amdhsa_exception_fp_ieee_div_zero 0
		.amdhsa_exception_fp_ieee_overflow 0
		.amdhsa_exception_fp_ieee_underflow 0
		.amdhsa_exception_fp_ieee_inexact 0
		.amdhsa_exception_int_div_zero 0
	.end_amdhsa_kernel

amdhsa.kernels:
  - .agpr_count:     0
    .args:
      - .offset:         0
        .size:           288
        .value_kind:     by_value
      - .offset:         288
        .size:           4
        .value_kind:     hidden_block_count_x
      - .offset:         292
        .size:           4
        .value_kind:     hidden_block_count_y
      - .offset:         296
        .size:           4
        .value_kind:     hidden_block_count_z
      - .offset:         300
        .size:           2
        .value_kind:     hidden_group_size_x
      - .offset:         302
        .size:           2
        .value_kind:     hidden_group_size_y
      - .offset:         304
        .size:           2
        .value_kind:     hidden_group_size_z
      - .offset:         306
        .size:           2
        .value_kind:     hidden_remainder_x
      - .offset:         308
        .size:           2
        .value_kind:     hidden_remainder_y
      - .offset:         310
        .size:           2
        .value_kind:     hidden_remainder_z
      - .offset:         328
        .size:           8
        .value_kind:     hidden_global_offset_x
      - .offset:         336
        .size:           8
        .value_kind:     hidden_global_offset_y
      - .offset:         344
        .size:           8
        .value_kind:     hidden_global_offset_z
      - .offset:         352
        .size:           2
        .value_kind:     hidden_grid_dims
      - .offset:         376
        .size:           8
        .value_kind:     hidden_multigrid_sync_arg
      - .offset:         408
        .size:           4
        .value_kind:     hidden_dynamic_lds_size
    .group_segment_fixed_size: 0
    .kernarg_segment_align: 8
    .kernarg_segment_size: 544
    .language:       OpenCL C
    .language_version:
      - 2
      - 0
    .max_flat_workgroup_size: 512
    .name:           _Z10fwd_kernel1P
    .private_segment_fixed_size: 0
    .sgpr_count:     108
    .sgpr_spill_count: 159
    .symbol:         _Z10fwd_kernel1P.kd
    .uniform_work_group_size: 1
    .uses_dynamic_stack: false
    .vgpr_count:     256
    .vgpr_spill_count: 0
    .wavefront_size: 64
